# grid barrier inside phase 4 replaced by a workgroup barrier: compressed-attention and selected/window attention task lists re-dealt so a workgroup only consumes masks/partials it produced (13 grid bar
# speedup vs baseline: 1.0153x; 1.0018x over previous
.LBB0_2003:
	s_cmp_lt_i32 s86, 5
	s_cselect_b64 s[66:67], -1, 0
	s_and_b64 s[0:1], s[66:67], s[0:1]
	s_andn2_b64 vcc, exec, s[0:1]
	s_cbranch_vccnz .LBB0_2170
	v_writelane_b32 v251, s66, 44
	s_add_u32 s0, s96, 0x2e00000
	v_and_b32_e32 v0, 7, v153
	v_writelane_b32 v251, s67, 45
	v_writelane_b32 v251, s88, 46
	v_lshlrev_b32_e32 v1, 3, v0
	v_and_b32_e32 v99, 15, v153
	v_writelane_b32 v251, s89, 47
	v_writelane_b32 v251, s86, 48
	v_lshrrev_b32_e32 v39, 4, v152
	v_lshrrev_b32_e32 v98, 3, v153
	v_writelane_b32 v251, s87, 49
	v_writelane_b32 v251, s84, 40
	v_writelane_b32 v251, s0, 50
	s_addc_u32 s0, s97, 0
	s_mov_b32 s19, s85
	v_writelane_b32 v251, s0, 51
	s_cmpk_gt_i32 s90, 0x1ff
	s_waitcnt vmcnt(0)
	v_mov_b32_e32 v37, 0
	v_lshlrev_b32_e32 v192, 4, v0
	v_lshlrev_b32_e32 v193, 3, v39
	v_and_b32_e32 v154, 48, v153
	v_lshlrev_b32_e32 v194, 2, v39
	v_mul_u32_u24_e32 v195, 0x90, v99
	v_mul_u32_u24_e32 v196, 0x90, v98
	v_lshlrev_b32_e32 v156, 1, v1
	v_mbcnt_lo_u32_b32 v155, -1, 0
	v_writelane_b32 v251, s90, 43
	s_cbranch_scc1 .LBB0_2011
	v_mov_b32_e32 v157, v37
	v_lshl_add_u64 v[0:1], s[96:97], 0, v[156:157]
	s_mov_b64 s[0:1], 0x2d00000
	v_lshlrev_b32_e32 v36, 4, v99
	v_lshl_add_u64 v[40:41], v[0:1], 0, s[0:1]
	v_lshl_add_u64 v[0:1], s[96:97], 0, v[36:37]
	s_mov_b64 s[0:1], 0x2d80000
	v_lshl_add_u64 v[42:43], v[0:1], 0, s[0:1]
	v_cmp_lt_u32_e64 s[0:1], 31, v152
	v_or_b32_e32 v38, 4, v39
	v_or_b32_e32 v45, 8, v39
	v_writelane_b32 v251, s0, 41
	v_or_b32_e32 v44, 12, v39
	v_or_b32_e32 v2, 0x70, v152
	v_writelane_b32 v251, s1, 42
	v_cmp_lt_u32_e64 s[0:1], 5, v38
	v_or_b32_e32 v47, 16, v39
	v_or_b32_e32 v0, 48, v152
	v_writelane_b32 v251, s0, 52
	v_mul_u32_u24_e32 v5, 0x90, v2
	v_mbcnt_hi_u32_b32 v2, -1, v155
	v_writelane_b32 v251, s1, 53
	v_cmp_lt_u32_e64 s[0:1], 9, v45
	v_mul_u32_u24_e32 v3, 0x90, v0
	v_mul_u32_u24_e32 v8, 0x110, v0
	v_writelane_b32 v251, s0, 54
	v_or_b32_e32 v46, 20, v39
	v_add_u32_e32 v0, 48, v153
	v_writelane_b32 v251, s1, 55
	v_cmp_lt_u32_e64 s[0:1], 13, v44
	v_and_b32_e32 v4, 64, v2
	v_and_or_b32 v0, v0, 63, v4
	v_writelane_b32 v251, s0, 56
	v_lshlrev_b32_e32 v141, 2, v0
	v_or_b32_e32 v0, v4, v99
	v_writelane_b32 v251, s1, 57
	v_cmp_lt_u32_e64 s[0:1], 17, v47
	v_lshlrev_b32_e32 v142, 2, v0
	v_xor_b32_e32 v0, 16, v2
	v_writelane_b32 v251, s0, 58
	v_add_u32_e32 v4, 64, v4
	v_cmp_lt_i32_e32 vcc, v0, v4
	v_writelane_b32 v251, s1, 59
	v_cmp_lt_u32_e64 s[0:1], 21, v46
	v_cndmask_b32_e32 v0, v2, v0, vcc
	v_lshlrev_b32_e32 v146, 2, v0
	v_writelane_b32 v251, s0, 60
	v_xor_b32_e32 v0, 32, v2
	v_cmp_lt_i32_e32 vcc, v0, v4
	v_writelane_b32 v251, s1, 61
	s_movk_i32 s0, 0x100
	v_lshlrev_b32_e64 v134, v39, s0
	s_movk_i32 s0, 0x1000
	v_lshlrev_b32_e64 v135, v39, s0
	s_mov_b32 s0, 0x10000
	v_lshlrev_b32_e64 v136, v39, s0
	s_mov_b32 s0, 0x100000
	v_lshlrev_b32_e64 v137, v39, s0
	s_mov_b32 s0, 0x1000000
	v_add_u32_e32 v6, 0x200, v153
	v_lshlrev_b32_e64 v138, v39, s0
	s_brev_b32 s0, 8
	v_cndmask_b32_e32 v0, v2, v0, vcc
	v_lshrrev_b32_e32 v4, 4, v153
	v_lshrrev_b32_e32 v11, 3, v6
	v_lshrrev_b32_e32 v12, 4, v6
	v_add_u32_e32 v100, 0, v154
	v_add_u32_e32 v1, 0, v193
	v_mul_u32_u24_e32 v7, 0x110, v99
	v_or_b32_e32 v49, 24, v39
	v_or_b32_e32 v48, 28, v39
	v_lshlrev_b32_e64 v139, v39, s0
	v_add_u32_e32 v9, 0, v36
	v_add_u32_e32 v140, 0, v192
	v_lshlrev_b32_e32 v147, 2, v0
	v_lshlrev_b32_e32 v0, 6, v98
	v_lshlrev_b32_e32 v2, 7, v4
	v_mul_u32_u24_e32 v10, 0x110, v4
	v_lshlrev_b32_e32 v4, 6, v11
	v_mul_u32_u24_e32 v11, 0x90, v11
	v_lshlrev_b32_e32 v6, 7, v12
	v_mul_u32_u24_e32 v12, 0x110, v12
	v_readlane_b32 s0, v251, 7
	s_mov_b32 s91, 0
	v_or_b32_e32 v101, 1, v194
	v_or_b32_e32 v102, 2, v194
	v_or_b32_e32 v103, 3, v194
	v_or_b32_e32 v104, 16, v194
	v_or_b32_e32 v105, 17, v194
	v_or_b32_e32 v106, 18, v194
	v_or_b32_e32 v107, 19, v194
	v_or_b32_e32 v108, 32, v194
	v_or_b32_e32 v109, 33, v194
	v_or_b32_e32 v110, 34, v194
	v_or_b32_e32 v111, 35, v194
	v_or_b32_e32 v112, 48, v194
	v_or_b32_e32 v113, 49, v194
	v_or_b32_e32 v114, 50, v194
	v_or_b32_e32 v115, 51, v194
	v_or_b32_e32 v116, 64, v194
	v_or_b32_e32 v117, 0x41, v194
	v_or_b32_e32 v118, 0x42, v194
	v_or_b32_e32 v119, 0x43, v194
	v_or_b32_e32 v120, 0x50, v194
	v_or_b32_e32 v121, 0x51, v194
	v_or_b32_e32 v122, 0x52, v194
	v_or_b32_e32 v123, 0x53, v194
	v_or_b32_e32 v124, 0x60, v194
	v_or_b32_e32 v125, 0x61, v194
	v_or_b32_e32 v126, 0x62, v194
	v_or_b32_e32 v127, 0x63, v194
	v_or_b32_e32 v128, 0x70, v194
	v_or_b32_e32 v129, 0x71, v194
	v_or_b32_e32 v130, 0x72, v194
	v_or_b32_e32 v131, 0x73, v194
	v_cmp_gt_u32_e64 s[2:3], 16, v152
	v_cmp_lt_u32_e64 s[4:5], 15, v152
	v_cmp_eq_u32_e64 s[8:9], 3, v39
	v_cmp_lt_u32_e64 s[20:21], 25, v49
	v_cmp_lt_u32_e64 s[22:23], 29, v48
	v_lshlrev_b32_e64 v132, v39, 1
	v_lshlrev_b32_e64 v133, v39, 16
	v_or_b32_e32 v143, 64, v142
	v_or_b32_e32 v144, 0x80, v142
	v_or_b32_e32 v145, 0xc0, v142
	s_lshl_b32 s7, s0, 4
	v_or_b32_e32 v50, 0x9000040, v193
	v_mov_b32_e32 v51, v37
	v_lshlrev_b32_e32 v52, 1, v0
	v_lshlrev_b32_e32 v54, 1, v2
	v_add_u32_e32 v148, v9, v10
	v_lshlrev_b32_e32 v56, 1, v4
	v_add_u32_e32 v149, v140, v11
	v_lshlrev_b32_e32 v58, 1, v6
	v_add_u32_e32 v150, v9, v12
	s_mov_b32 s6, 0x3e000000
	v_add_u32_e32 v151, v100, v3
	v_add_u32_e32 v157, v100, v5
	v_add_u32_e32 v158, v1, v7
	v_add_u32_e32 v159, v1, v8
	s_mov_b64 s[10:11], 0x80
	v_mov_b32_e32 v160, 0xf149f2ca
	v_mov_b32_e32 v161, 0x461c4000
	v_readlane_b32 s33, v251, 43
	s_and_b32 s0, s33, 7
	s_lshl_b32 s0, s0, 4
	s_bfe_u32 s1, s33, 0x40003
	s_or_b32 s0, s0, s1
	s_lshr_b32 s1, s33, 7
	s_lshl_b32 s1, s1, 8
	s_or_b32 s33, s0, s1
	s_lshl_b32 s95, s33, 3
	s_branch .LBB0_2007
.LBB0_2006:
	s_or_b64 exec, exec, s[0:1]
	s_bitcmp1_b32 s33, 7
	s_cbranch_scc1 .LBB0_2011
	s_and_b32 s0, s33, 15
	s_andn2_b32 s33, s33, 15
	s_sub_i32 s0, 0x8f, s0
	s_add_i32 s33, s33, s0
	s_lshl_b32 s95, s33, 3

.LBB0_2011:
	s_waitcnt vmcnt(0)
	s_waitcnt lgkmcnt(0)
	s_barrier
	s_mov_b64 s[0:1], exec
	v_readlane_b32 s2, v251, 1
	v_readlane_b32 s3, v251, 2
	v_readlane_b32 s86, v251, 48
	v_readlane_b32 s72, v251, 3
	v_readlane_b32 s66, v251, 44
	s_and_b64 s[2:3], s[0:1], s[2:3]
	v_readlane_b32 s84, v251, 40
	v_readlane_b32 s87, v251, 49
	v_readlane_b32 s88, v251, 46
	v_readlane_b32 s73, v251, 4
	v_readlane_b32 s74, v251, 5
	v_readlane_b32 s75, v251, 6
	v_readlane_b32 s90, v251, 43
	s_mov_b32 s23, s19
	v_readlane_b32 s67, v251, 45
	v_readlane_b32 s89, v251, 47
.LBB0_2063:
	s_or_b64 exec, exec, s[0:1]
	s_cmpk_gt_i32 s90, 0x3ff
	v_readlane_b32 s68, v251, 50
	v_readlane_b32 s69, v251, 51
	s_waitcnt lgkmcnt(0)
	s_barrier
	s_cbranch_scc1 .LBB0_2167
	v_readlane_b32 s0, v251, 7
	v_and_b32_e32 v112, 15, v152
	v_lshrrev_b32_e32 v113, 4, v152
	s_nop 1
	s_and_b32 s34, s0, 3
	s_lshr_b32 s35, s0, 2
	v_lshrrev_b32_e32 v220, 3, v153
	v_and_b32_e32 v221, 7, v153
	v_and_b32_e32 v222, 7, v220
	v_xor_b32_e32 v222, v222, v221
	v_lshlrev_b32_e32 v222, 4, v222
	v_lshl_add_u32 v114, v220, 7, v222
	v_mul_u32_u24_e32 v123, 0x90, v220
	v_lshl_add_u32 v123, v221, 4, v123
	v_add_u32_e32 v123, 0x2400, v123
	v_mul_u32_u24_e32 v117, 0x600, v220
	v_lshl_add_u32 v117, v221, 4, v117
	v_lshlrev_b32_e32 v118, 12, v220
	v_lshl_add_u32 v118, v221, 4, v118
	v_mul_u32_u24_e32 v116, 0x90, v112
	v_lshl_add_u32 v116, v113, 3, v116
	v_and_b32_e32 v222, 7, v112
	v_xor_b32_e32 v222, v222, v113
	v_lshlrev_b32_e32 v222, 4, v222
	v_lshl_add_u32 v115, v112, 7, v222
	v_xor_b32_e32 v122, 64, v115
	s_lshl_b32 s1, s0, 13
	s_add_i32 s1, s1, 0x9000
	v_lshl_add_u32 v250, v152, 4, s1
	v_mov_b32_e32 v226, 0xf149f2ca
	v_mov_b32_e32 v227, 0xff61b1e6
	v_mov_b32_e32 v203, 0x41000000
	v_mov_b32_e32 v238, 0
	v_mov_b32_e32 v224, 0xff800000
	s_mov_b32 s26, s90
	s_mov_b32 s50, 0
.Lnsa_task:
	s_lshr_b32 s65, s26, 8
	s_and_b32 s1, s26, 255
	s_bfe_u32 s28, s1, 0x40003
	s_lshl_b32 s28, s28, 1
	s_lshr_b32 s2, s65, 1
	s_add_i32 s28, s28, s2
	s_sub_i32 s2, 31, s28
	s_bitcmp1_b32 s65, 0
	s_cselect_b32 s28, s2, s28
	s_and_b32 s29, s1, 7
	s_lshr_b32 s2, s1, 7
	s_lshl_b32 s2, s2, 4
	s_add_i32 s29, s29, s2
	s_and_b32 s2, s65, 1
	s_lshl_b32 s2, s2, 3
	s_add_i32 s29, s29, s2
	s_lshr_b32 s30, s29, 1
	s_and_b32 s31, s29, 1
	s_lshl_b32 s36, s31, 2
	s_add_i32 s36, s36, s34
	s_lshl_b32 s33, s28, 6
	s_mov_b32 s32, s28
	s_lshl_b32 s2, s35, 5
	s_add_i32 s2, s2, s33
	v_add_u32_e32 v86, s2, v112
	v_add_u32_e32 v87, 16, v86
	s_lshl_b32 s6, s29, 11
	s_add_i32 s7, s6, s33
	v_add_u32_e32 v221, s7, v152
	v_lshlrev_b32_e32 v221, 2, v221
	s_add_u32 s4, s96, 0x2e00000
	s_addc_u32 s5, s97, 0
	global_load_dword v243, v221, s[4:5]
	s_lshl_b32 s3, s30, 11
	v_add_u32_e32 v220, s3, v86
	v_lshlrev_b32_e32 v234, 10, v220
	s_lshl_b32 s4, s36, 7
	v_add_u32_e32 v234, s4, v234
	v_lshl_add_u32 v234, v113, 4, v234
	v_mov_b32_e32 v235, 0
	s_add_u32 s4, s96, 0xe000000
	s_addc_u32 s5, s97, 0
	v_lshl_add_u64 v[234:235], s[4:5], 0, v[234:235]
	global_load_dwordx4 v[160:163], v[234:235], off
	global_load_dwordx4 v[164:167], v[234:235], off offset:64
	v_lshlrev_b32_e32 v236, 8, v86
	v_lshl_add_u32 v236, v113, 6, v236
	s_add_u32 s4, s96, 0x2c00000
	s_addc_u32 s5, s97, 0
	global_load_dwordx4 v[124:127], v236, s[4:5] offset:0
	global_load_dwordx4 v[128:131], v236, s[4:5] offset:16
	global_load_dwordx4 v[132:135], v236, s[4:5] offset:32
	global_load_dwordx4 v[136:139], v236, s[4:5] offset:48
	s_lshl_b32 s6, s29, 11
	v_add_u32_e32 v221, s6, v86
	v_lshlrev_b32_e32 v221, 2, v221
	s_add_u32 s4, s96, 0x2e00000
	s_addc_u32 s5, s97, 0
	global_load_dword v84, v221, s[4:5]
	v_add_u32_e32 v220, s3, v87
	v_lshlrev_b32_e32 v234, 10, v220
	s_lshl_b32 s4, s36, 7
	v_add_u32_e32 v234, s4, v234
	v_lshl_add_u32 v234, v113, 4, v234
	v_mov_b32_e32 v235, 0
	s_add_u32 s4, s96, 0xe000000
	s_addc_u32 s5, s97, 0
	v_lshl_add_u64 v[234:235], s[4:5], 0, v[234:235]
	global_load_dwordx4 v[168:171], v[234:235], off
	global_load_dwordx4 v[172:175], v[234:235], off offset:64
	v_lshlrev_b32_e32 v236, 8, v87
	v_lshl_add_u32 v236, v113, 6, v236
	s_add_u32 s4, s96, 0x2c00000
	s_addc_u32 s5, s97, 0
	global_load_dwordx4 v[140:143], v236, s[4:5] offset:0
	global_load_dwordx4 v[144:147], v236, s[4:5] offset:16
	global_load_dwordx4 v[148:151], v236, s[4:5] offset:32
	global_load_dwordx4 v[154:157], v236, s[4:5] offset:48
	s_lshl_b32 s6, s29, 11
	v_add_u32_e32 v221, s6, v87
	v_lshlrev_b32_e32 v221, 2, v221
	s_add_u32 s4, s96, 0x2e00000
	s_addc_u32 s5, s97, 0
	global_load_dword v85, v221, s[4:5]
	s_lshl_b32 s3, s30, 11
	s_mul_i32 s2, s36, 6
	s_add_i32 s2, s2, 2
	s_add_u32 s8, s96, 0x13000000
	s_addc_u32 s9, s97, 0
	v_add_u32_e32 v223, s3, v86
	v_lshlrev_b32_e32 v223, 6, v223
	v_add_u32_e32 v223, s2, v223
	global_load_ushort v119, v223, s[8:9]
	global_load_ushort v158, v223, s[8:9] offset:2
	v_add_u32_e32 v223, s3, v87
	v_lshlrev_b32_e32 v223, 6, v223
	v_add_u32_e32 v223, s2, v223
	global_load_ushort v159, v223, s[8:9]
	global_load_ushort v233, v223, s[8:9] offset:2
	s_add_u32 s8, s96, 0x9000000
	s_addc_u32 s9, s97, 0
	v_add_u32_e32 v223, s3, v86
	v_lshlrev_b32_e32 v223, 10, v223
	s_lshl_b32 s2, s36, 7
	v_add_u32_e32 v223, s2, v223
	v_lshl_add_u32 v223, v113, 3, v223
	global_load_dwordx2 v[16:17], v223, s[8:9] offset:0
	global_load_dwordx2 v[20:21], v223, s[8:9] offset:32
	global_load_dwordx2 v[24:25], v223, s[8:9] offset:64
	global_load_dwordx2 v[28:29], v223, s[8:9] offset:96
	v_add_u32_e32 v223, s3, v87
	v_lshlrev_b32_e32 v223, 10, v223
	s_lshl_b32 s2, s36, 7
	v_add_u32_e32 v223, s2, v223
	v_lshl_add_u32 v223, v113, 3, v223
	global_load_dwordx2 v[32:33], v223, s[8:9] offset:0
	global_load_dwordx2 v[36:37], v223, s[8:9] offset:32
	global_load_dwordx2 v[40:41], v223, s[8:9] offset:64
	global_load_dwordx2 v[44:45], v223, s[8:9] offset:96
	s_mul_i32 s2, s30, 0x300000
	s_add_u32 s8, s96, 0x10000000
	s_addc_u32 s9, s97, 0
	s_add_u32 s8, s8, s2
	s_addc_u32 s9, s9, 0
	s_lshl_b32 s2, s31, 7
	s_add_u32 s8, s8, s2
	s_addc_u32 s9, s9, 0
	s_add_u32 s10, s8, 0x200
	s_addc_u32 s11, s9, 0
	global_load_dwordx4 v[88:91], v117, s[10:11]
	s_lshl_b32 s2, s29, 18
	s_add_u32 s10, s96, 0x1b200000
	s_addc_u32 s11, s97, 0
	s_add_u32 s10, s10, s2
	s_addc_u32 s11, s11, 0
	global_load_dwordx4 v[92:95], v118, s[10:11]
	s_add_i32 s12, s32, -8
	s_max_i32 s12, s12, 0
	s_mul_i32 s13, s12, 0x18000
	s_add_u32 s10, s8, 0x400
	s_addc_u32 s11, s9, 0
	s_add_u32 s10, s10, s13
	s_addc_u32 s11, s11, 0
	global_load_dwordx4 v[192:195], v117, s[10:11]
	s_lshl_b32 s13, s12, 7
	s_add_u32 s10, s96, 0x1ba00000
	s_addc_u32 s11, s97, 0
	s_add_u32 s10, s10, s2
	s_addc_u32 s11, s11, 0
	s_add_u32 s10, s10, s13
	s_addc_u32 s11, s11, 0
	global_load_dwordx4 v[196:199], v118, s[10:11]
	s_waitcnt vmcnt(30)
	s_nop 0
	v_or_b32_dpp v243, v243, v243 quad_perm:[1,0,3,2] row_mask:0xf bank_mask:0xf bound_ctrl:1
	s_nop 1
	v_or_b32_dpp v243, v243, v243 quad_perm:[2,3,0,1] row_mask:0xf bank_mask:0xf bound_ctrl:1
	s_nop 1
	v_or_b32_dpp v243, v243, v243 row_ror:4 row_mask:0xf bank_mask:0xf bound_ctrl:1
	s_nop 1
	v_or_b32_dpp v243, v243, v243 row_ror:8 row_mask:0xf bank_mask:0xf bound_ctrl:1
	v_mov_b32_e32 v242, v243
	s_nop 1
	v_permlane16_swap_b32_e32 v243, v242
	v_or_b32_e32 v243, v243, v242
	v_mov_b32_e32 v242, v243
	s_nop 1
	v_permlane32_swap_b32_e32 v243, v242
	v_or_b32_e32 v243, v243, v242
	s_nop 0
	v_readfirstlane_b32 s39, v243
	s_add_u32 s46, s8, 0x200
	s_addc_u32 s47, s9, 0
	s_lshl_b32 s2, s29, 18
	s_add_u32 s48, s96, 0x1b200000
	s_addc_u32 s49, s97, 0
	s_add_u32 s48, s48, s2
	s_addc_u32 s49, s49, 0
	s_lshl_b32 s2, 2, s32
	s_add_i32 s2, s2, -1
	s_and_b32 s38, s39, s2
	s_ff1_i32_b32 s15, s38
	s_add_i32 s65, s38, -1
	s_and_b32 s38, s38, s65
	s_ff1_i32_b32 s41, s38
	s_add_i32 s65, s38, -1
	s_and_b32 s38, s38, s65
	s_ff1_i32_b32 s42, s38
	s_add_i32 s65, s38, -1
	s_and_b32 s38, s38, s65
	s_cmp_eq_u32 s15, 0
	s_cbranch_scc1 .Lnsa_e0_1
	s_mov_b32 s40, s15
	s_max_i32 s65, s40, 0
	s_mul_i32 s56, s65, 0x18000
	s_lshl_b32 s58, s65, 7
	s_add_u32 s56, s46, s56
	s_addc_u32 s57, s47, 0
	s_add_u32 s58, s48, s58
	s_addc_u32 s59, s49, 0
	global_load_dwordx4 v[88:91], v117, s[56:57]
	global_load_dwordx4 v[92:95], v118, s[58:59]
